# sp2 up-projection: row-sum loads for 1/rms issued at phase entry and consumed behind the first tile's load wait
# speedup vs baseline: 1.0062x; 1.0062x over previous
.Lg2_up_entry:
	s_waitcnt vmcnt(0) lgkmcnt(0)
	s_barrier
	v_mov_b32_e32 v2, 0x10200
	ds_read_b64 v[2:3], v2
	v_readlane_b32 s0, v246, 0
	v_lshrrev_b32_e32 v4, 6, v163
	v_and_b32_e32 v5, 63, v163
	s_and_b32 s1, s0, 7
	s_lshr_b32 s0, s0, 3
	s_lshr_b32 s68, s0, 3
	s_and_b32 s0, s0, 7
	s_lshl_b32 s0, s0, 3
	s_add_i32 s0, s0, s1
	s_cmp_lt_u32 s0, 32
	s_cselect_b32 s43, 1, 0
	s_min_u32 s1, s0, 32
	s_lshl_b32 s0, s0, 4
	s_add_i32 s0, s0, s1
	s_lshl_b32 s42, s0, 4
	v_readfirstlane_b32 s70, v4
	v_and_b32_e32 v6, 15, v5
	v_lshrrev_b32_e32 v7, 4, v5
	s_waitcnt lgkmcnt(0)
	v_readfirstlane_b32 s66, v2
	v_readfirstlane_b32 s67, v3
	s_lshl_b32 s62, s70, 10
	v_and_b32_e32 v8, 7, v6
	v_xor_b32_e32 v9, v7, v8
	v_lshlrev_b32_e32 v9, 4, v9
	v_lshl_add_u32 v156, v6, 7, v9
	v_add_u32_e32 v10, 4, v7
	v_xor_b32_e32 v10, v10, v8
	v_lshlrev_b32_e32 v10, 4, v10
	v_lshl_add_u32 v157, v6, 7, v10
	v_add_u32_e32 v158, 0x8800, v156
	v_add_u32_e32 v159, 0x8800, v157
	v_lshrrev_b32_e32 v11, 3, v163
	v_and_b32_e32 v12, 7, v163
	v_and_b32_e32 v13, 7, v11
	v_xor_b32_e32 v12, v12, v13
	v_lshlrev_b32_e32 v12, 4, v12
	s_mov_b32 s2, 0x3900
	v_mul_lo_u32 v11, v11, s2
	v_add_u32_e32 v162, v11, v12
	v_lshrrev_b32_e32 v11, 4, v163
	v_and_b32_e32 v12, 15, v163
	v_xor_b32_e32 v13, v12, v11
	v_lshlrev_b32_e32 v13, 4, v13
	v_lshl_add_u32 v247, v11, 8, v13
	s_mov_b32 s2, 0x600
	v_mul_lo_u32 v11, v11, s2
	v_lshl_add_u32 v252, v12, 4, v11
	v_add_u32_e32 v255, 0x8000, v247
	v_lshlrev_b32_e32 v11, 1, v4
	s_mov_b32 s2, 0x2000
	v_mul_lo_u32 v12, v11, s2
	v_lshl_add_u32 v160, v5, 4, v12
	v_add_u32_e32 v161, 0x2000, v160
	v_lshrrev_b32_e32 v12, 1, v7
	v_lshl_add_u32 v12, v11, 1, v12
	v_and_b32_e32 v13, 1, v7
	v_lshlrev_b32_e32 v13, 3, v13
	v_lshl_add_u32 v14, v6, 8, v13
	v_xor_b32_e32 v15, v12, v6
	v_lshlrev_b32_e32 v15, 4, v15
	v_add_u32_e32 v212, v14, v15
	v_add_u32_e32 v12, 2, v12
	v_xor_b32_e32 v15, v12, v6
	v_lshlrev_b32_e32 v15, 4, v15
	v_add_u32_e32 v213, v14, v15
	v_add_u32_e32 v253, 0x8000, v212
	v_add_u32_e32 v254, 0x8000, v213
	s_lshl_b32 s0, s42, 2
	s_add_u32 s0, s0, 0x16c00000
	s_add_u32 s0, s26, s0
	s_addc_u32 s1, s27, 0
	s_add_u32 s2, s0, 0x11000
	s_addc_u32 s3, s1, 0
	s_add_u32 s4, s2, 0x11000
	s_addc_u32 s5, s3, 0
	s_add_u32 s6, s4, 0x11000
	s_addc_u32 s7, s5, 0
	v_lshlrev_b32_e32 v8, 2, v163
	global_load_dword v200, v8, s[0:1]
	global_load_dword v201, v8, s[2:3]
	global_load_dword v202, v8, s[4:5]
	global_load_dword v203, v8, s[6:7]
	global_load_dword v204, v8, s[0:1] offset:1024
	global_load_dword v205, v8, s[2:3] offset:1024
	global_load_dword v206, v8, s[4:5] offset:1024
	global_load_dword v207, v8, s[6:7] offset:1024
	v_add_u32_e32 v208, 0x11000, v8
	s_mov_b32 s64, 0

.Lg2_up_nodma_1:
	v_mov_b32_e32 v0, 0
	v_mov_b32_e32 v1, 0
	v_mov_b32_e32 v2, 0
	v_mov_b32_e32 v3, 0
	v_mov_b32_e32 v4, 0
	v_mov_b32_e32 v5, 0
	v_mov_b32_e32 v6, 0
	v_mov_b32_e32 v7, 0
	v_mov_b32_e32 v8, 0
	v_mov_b32_e32 v9, 0
	v_mov_b32_e32 v10, 0
	v_mov_b32_e32 v11, 0
	v_mov_b32_e32 v12, 0
	v_mov_b32_e32 v13, 0
	v_mov_b32_e32 v14, 0
	v_mov_b32_e32 v15, 0
	v_mov_b32_e32 v16, 0
	v_mov_b32_e32 v17, 0
	v_mov_b32_e32 v18, 0
	v_mov_b32_e32 v19, 0
	v_mov_b32_e32 v20, 0
	v_mov_b32_e32 v21, 0
	v_mov_b32_e32 v22, 0
	v_mov_b32_e32 v23, 0
	v_mov_b32_e32 v24, 0
	v_mov_b32_e32 v25, 0
	v_mov_b32_e32 v26, 0
	v_mov_b32_e32 v27, 0
	v_mov_b32_e32 v28, 0
	v_mov_b32_e32 v29, 0
	v_mov_b32_e32 v30, 0
	v_mov_b32_e32 v31, 0
	v_mov_b32_e32 v32, 0
	v_mov_b32_e32 v33, 0
	v_mov_b32_e32 v34, 0
	v_mov_b32_e32 v35, 0
	v_mov_b32_e32 v36, 0
	v_mov_b32_e32 v37, 0
	v_mov_b32_e32 v38, 0
	v_mov_b32_e32 v39, 0
	v_mov_b32_e32 v40, 0
	v_mov_b32_e32 v41, 0
	v_mov_b32_e32 v42, 0
	v_mov_b32_e32 v43, 0
	v_mov_b32_e32 v44, 0
	v_mov_b32_e32 v45, 0
	v_mov_b32_e32 v46, 0
	v_mov_b32_e32 v47, 0
	v_mov_b32_e32 v48, 0
	v_mov_b32_e32 v49, 0
	v_mov_b32_e32 v50, 0
	v_mov_b32_e32 v51, 0
	v_mov_b32_e32 v52, 0
	v_mov_b32_e32 v53, 0
	v_mov_b32_e32 v54, 0
	v_mov_b32_e32 v55, 0
	v_mov_b32_e32 v56, 0
	v_mov_b32_e32 v57, 0
	v_mov_b32_e32 v58, 0
	v_mov_b32_e32 v59, 0
	v_mov_b32_e32 v60, 0
	v_mov_b32_e32 v61, 0
	v_mov_b32_e32 v62, 0
	v_mov_b32_e32 v63, 0
	v_mov_b32_e32 v64, 0
	v_mov_b32_e32 v65, 0
	v_mov_b32_e32 v66, 0
	v_mov_b32_e32 v67, 0
	v_mov_b32_e32 v68, 0
	v_mov_b32_e32 v69, 0
	v_mov_b32_e32 v70, 0
	v_mov_b32_e32 v71, 0
	v_mov_b32_e32 v72, 0
	v_mov_b32_e32 v73, 0
	v_mov_b32_e32 v74, 0
	v_mov_b32_e32 v75, 0
	v_mov_b32_e32 v76, 0
	v_mov_b32_e32 v77, 0
	v_mov_b32_e32 v78, 0
	v_mov_b32_e32 v79, 0
	v_mov_b32_e32 v80, 0
	v_mov_b32_e32 v81, 0
	v_mov_b32_e32 v82, 0
	v_mov_b32_e32 v83, 0
	v_mov_b32_e32 v84, 0
	v_mov_b32_e32 v85, 0
	v_mov_b32_e32 v86, 0
	v_mov_b32_e32 v87, 0
	v_mov_b32_e32 v88, 0
	v_mov_b32_e32 v89, 0
	v_mov_b32_e32 v90, 0
	v_mov_b32_e32 v91, 0
	v_mov_b32_e32 v92, 0
	v_mov_b32_e32 v93, 0
	v_mov_b32_e32 v94, 0
	v_mov_b32_e32 v95, 0
	v_mov_b32_e32 v96, 0
	v_mov_b32_e32 v97, 0
	v_mov_b32_e32 v98, 0
	v_mov_b32_e32 v99, 0
	v_mov_b32_e32 v100, 0
	v_mov_b32_e32 v101, 0
	v_mov_b32_e32 v102, 0
	v_mov_b32_e32 v103, 0
	v_mov_b32_e32 v104, 0
	v_mov_b32_e32 v105, 0
	v_mov_b32_e32 v106, 0
	v_mov_b32_e32 v107, 0
	v_mov_b32_e32 v108, 0
	v_mov_b32_e32 v109, 0
	v_mov_b32_e32 v110, 0
	v_mov_b32_e32 v111, 0
	v_mov_b32_e32 v112, 0
	v_mov_b32_e32 v113, 0
	v_mov_b32_e32 v114, 0
	v_mov_b32_e32 v115, 0
	v_mov_b32_e32 v116, 0
	v_mov_b32_e32 v117, 0
	v_mov_b32_e32 v118, 0
	v_mov_b32_e32 v119, 0
	v_mov_b32_e32 v120, 0
	v_mov_b32_e32 v121, 0
	v_mov_b32_e32 v122, 0
	v_mov_b32_e32 v123, 0
	v_mov_b32_e32 v124, 0
	v_mov_b32_e32 v125, 0
	v_mov_b32_e32 v126, 0
	v_mov_b32_e32 v127, 0
	v_mov_b32_e32 v128, 0
	v_mov_b32_e32 v129, 0
	v_mov_b32_e32 v130, 0
	v_mov_b32_e32 v131, 0
	v_mov_b32_e32 v132, 0
	v_mov_b32_e32 v133, 0
	v_mov_b32_e32 v134, 0
	v_mov_b32_e32 v135, 0
	s_mov_b32 s63, 0
	s_waitcnt vmcnt(0)
	s_barrier
	s_cmp_lg_u32 s64, 0
	s_cbranch_scc1 .Lg2_up_rrskip1
	v_add_f32_e32 v200, v200, v201
	v_add_f32_e32 v202, v202, v203
	v_add_f32_e32 v204, v204, v205
	v_add_f32_e32 v206, v206, v207
	v_mul_f32_e32 v200, 0x3b800000, v200
	v_mul_f32_e32 v202, 0x3b800000, v202
	v_mul_f32_e32 v204, 0x3b800000, v204
	v_mul_f32_e32 v206, 0x3b800000, v206
	v_add_f32_e32 v200, 0x3727c5ac, v200
	v_add_f32_e32 v202, 0x3727c5ac, v202
	v_add_f32_e32 v204, 0x3727c5ac, v204
	v_add_f32_e32 v206, 0x3727c5ac, v206
	v_rsq_f32_e32 v200, v200
	v_rsq_f32_e32 v202, v202
	v_rsq_f32_e32 v204, v204
	v_rsq_f32_e32 v206, v206
	s_nop 0
	v_mul_f32_e32 v200, 0x3e16c740, v200
	v_mul_f32_e32 v204, 0x3e16c740, v204
	ds_write_b32 v208, v200
	ds_write_b32 v208, v202 offset:1088
	v_cmp_gt_u32_e32 vcc, 16, v163
	s_and_saveexec_b64 s[0:1], vcc
	ds_write_b32 v208, v204 offset:1024
	ds_write_b32 v208, v206 offset:2112
	s_mov_b64 exec, s[0:1]

.Lg2_up_k16:
	s_add_u32 m0, s62, 0x0
	s_add_u32 s4, s56, 0x0
	s_addc_u32 s5, s57, 0
	global_load_lds_dwordx4 v162, s[4:5]
	s_add_u32 m0, s62, 0x1000
	s_add_u32 s4, s56, 0x72000
	s_addc_u32 s5, s57, 0
	global_load_lds_dwordx4 v162, s[4:5]
	s_add_u32 m0, s62, 0x2000
	s_add_u32 s4, s56, 0xe4000
	s_addc_u32 s5, s57, 0
	global_load_lds_dwordx4 v162, s[4:5]
	s_add_u32 m0, s62, 0x3000
	s_add_u32 s4, s56, 0x156000
	s_addc_u32 s5, s57, 0
	global_load_lds_dwordx4 v162, s[4:5]
	s_add_u32 m0, s62, 0x4000
	s_add_u32 s4, s56, 0x1c8000
	s_addc_u32 s5, s57, 0
	global_load_lds_dwordx4 v162, s[4:5]
	s_add_u32 m0, s62, 0x5000
	s_add_u32 s4, s56, 0x23a000
	s_addc_u32 s5, s57, 0
	global_load_lds_dwordx4 v162, s[4:5]
	s_add_u32 m0, s62, 0x6000
	s_add_u32 s4, s56, 0x2ac000
	s_addc_u32 s5, s57, 0
	global_load_lds_dwordx4 v162, s[4:5]
	s_add_u32 m0, s62, 0x7000
	s_add_u32 s4, s56, 0x31e000
	s_addc_u32 s5, s57, 0
	global_load_lds_dwordx4 v162, s[4:5]
	global_load_dwordx4 v[184:187], v160, s[58:59] offset:0
	global_load_dwordx4 v[188:191], v160, s[58:59] offset:1024
	global_load_dwordx4 v[192:195], v161, s[58:59] offset:0
	global_load_dwordx4 v[196:199], v161, s[58:59] offset:1024
	s_add_u32 s56, s56, 0x80
	s_addc_u32 s57, s57, 0
	s_add_u32 m0, s62, 0x8800
	s_add_u32 s4, s56, 0x0
	s_addc_u32 s5, s57, 0
	global_load_lds_dwordx4 v162, s[4:5]
	s_add_u32 m0, s62, 0x9800
	s_add_u32 s4, s56, 0x72000
	s_addc_u32 s5, s57, 0
	global_load_lds_dwordx4 v162, s[4:5]
	s_add_u32 m0, s62, 0xa800
	s_add_u32 s4, s56, 0xe4000
	s_addc_u32 s5, s57, 0
	global_load_lds_dwordx4 v162, s[4:5]
	s_add_u32 m0, s62, 0xb800
	s_add_u32 s4, s56, 0x156000
	s_addc_u32 s5, s57, 0
	global_load_lds_dwordx4 v162, s[4:5]
	s_add_u32 m0, s62, 0xc800
	s_add_u32 s4, s56, 0x1c8000
	s_addc_u32 s5, s57, 0
	global_load_lds_dwordx4 v162, s[4:5]
	s_add_u32 m0, s62, 0xd800
	s_add_u32 s4, s56, 0x23a000
	s_addc_u32 s5, s57, 0
	global_load_lds_dwordx4 v162, s[4:5]
	s_add_u32 m0, s62, 0xe800
	s_add_u32 s4, s56, 0x2ac000
	s_addc_u32 s5, s57, 0
	global_load_lds_dwordx4 v162, s[4:5]
	s_add_u32 m0, s62, 0xf800
	s_add_u32 s4, s56, 0x31e000
	s_addc_u32 s5, s57, 0
	global_load_lds_dwordx4 v162, s[4:5]
	v_mov_b32_e32 v0, 0
	v_mov_b32_e32 v1, 0
	v_mov_b32_e32 v2, 0
	v_mov_b32_e32 v3, 0
	v_mov_b32_e32 v4, 0
	v_mov_b32_e32 v5, 0
	v_mov_b32_e32 v6, 0
	v_mov_b32_e32 v7, 0
	v_mov_b32_e32 v8, 0
	v_mov_b32_e32 v9, 0
	v_mov_b32_e32 v10, 0
	v_mov_b32_e32 v11, 0
	v_mov_b32_e32 v12, 0
	v_mov_b32_e32 v13, 0
	v_mov_b32_e32 v14, 0
	v_mov_b32_e32 v15, 0
	v_mov_b32_e32 v16, 0
	v_mov_b32_e32 v17, 0
	v_mov_b32_e32 v18, 0
	v_mov_b32_e32 v19, 0
	v_mov_b32_e32 v20, 0
	v_mov_b32_e32 v21, 0
	v_mov_b32_e32 v22, 0
	v_mov_b32_e32 v23, 0
	v_mov_b32_e32 v24, 0
	v_mov_b32_e32 v25, 0
	v_mov_b32_e32 v26, 0
	v_mov_b32_e32 v27, 0
	v_mov_b32_e32 v28, 0
	v_mov_b32_e32 v29, 0
	v_mov_b32_e32 v30, 0
	v_mov_b32_e32 v31, 0
	v_mov_b32_e32 v32, 0
	v_mov_b32_e32 v33, 0
	v_mov_b32_e32 v34, 0
	v_mov_b32_e32 v35, 0
	v_mov_b32_e32 v36, 0
	v_mov_b32_e32 v37, 0
	v_mov_b32_e32 v38, 0
	v_mov_b32_e32 v39, 0
	v_mov_b32_e32 v40, 0
	v_mov_b32_e32 v41, 0
	v_mov_b32_e32 v42, 0
	v_mov_b32_e32 v43, 0
	v_mov_b32_e32 v44, 0
	v_mov_b32_e32 v45, 0
	v_mov_b32_e32 v46, 0
	v_mov_b32_e32 v47, 0
	v_mov_b32_e32 v48, 0
	v_mov_b32_e32 v49, 0
	v_mov_b32_e32 v50, 0
	v_mov_b32_e32 v51, 0
	v_mov_b32_e32 v52, 0
	v_mov_b32_e32 v53, 0
	v_mov_b32_e32 v54, 0
	v_mov_b32_e32 v55, 0
	v_mov_b32_e32 v56, 0
	v_mov_b32_e32 v57, 0
	v_mov_b32_e32 v58, 0
	v_mov_b32_e32 v59, 0
	v_mov_b32_e32 v60, 0
	v_mov_b32_e32 v61, 0
	v_mov_b32_e32 v62, 0
	v_mov_b32_e32 v63, 0
	v_mov_b32_e32 v64, 0
	v_mov_b32_e32 v65, 0
	v_mov_b32_e32 v66, 0
	v_mov_b32_e32 v67, 0
	v_mov_b32_e32 v68, 0
	v_mov_b32_e32 v69, 0
	v_mov_b32_e32 v70, 0
	v_mov_b32_e32 v71, 0
	v_mov_b32_e32 v72, 0
	v_mov_b32_e32 v73, 0
	v_mov_b32_e32 v74, 0
	v_mov_b32_e32 v75, 0
	v_mov_b32_e32 v76, 0
	v_mov_b32_e32 v77, 0
	v_mov_b32_e32 v78, 0
	v_mov_b32_e32 v79, 0
	v_mov_b32_e32 v80, 0
	v_mov_b32_e32 v81, 0
	v_mov_b32_e32 v82, 0
	v_mov_b32_e32 v83, 0
	v_mov_b32_e32 v84, 0
	v_mov_b32_e32 v85, 0
	v_mov_b32_e32 v86, 0
	v_mov_b32_e32 v87, 0
	v_mov_b32_e32 v88, 0
	v_mov_b32_e32 v89, 0
	v_mov_b32_e32 v90, 0
	v_mov_b32_e32 v91, 0
	v_mov_b32_e32 v92, 0
	v_mov_b32_e32 v93, 0
	v_mov_b32_e32 v94, 0
	v_mov_b32_e32 v95, 0
	v_mov_b32_e32 v96, 0
	v_mov_b32_e32 v97, 0
	v_mov_b32_e32 v98, 0
	v_mov_b32_e32 v99, 0
	v_mov_b32_e32 v100, 0
	v_mov_b32_e32 v101, 0
	v_mov_b32_e32 v102, 0
	v_mov_b32_e32 v103, 0
	v_mov_b32_e32 v104, 0
	v_mov_b32_e32 v105, 0
	v_mov_b32_e32 v106, 0
	v_mov_b32_e32 v107, 0
	v_mov_b32_e32 v108, 0
	v_mov_b32_e32 v109, 0
	v_mov_b32_e32 v110, 0
	v_mov_b32_e32 v111, 0
	v_mov_b32_e32 v112, 0
	v_mov_b32_e32 v113, 0
	v_mov_b32_e32 v114, 0
	v_mov_b32_e32 v115, 0
	v_mov_b32_e32 v116, 0
	v_mov_b32_e32 v117, 0
	v_mov_b32_e32 v118, 0
	v_mov_b32_e32 v119, 0
	v_mov_b32_e32 v120, 0
	v_mov_b32_e32 v121, 0
	v_mov_b32_e32 v122, 0
	v_mov_b32_e32 v123, 0
	v_mov_b32_e32 v124, 0
	v_mov_b32_e32 v125, 0
	v_mov_b32_e32 v126, 0
	v_mov_b32_e32 v127, 0
	s_mov_b32 s63, 0
	s_waitcnt vmcnt(0)
	s_barrier
	s_cmp_lg_u32 s64, 0
	s_cbranch_scc1 .Lg2_up_rrskip2
	v_add_f32_e32 v200, v200, v201
	v_add_f32_e32 v202, v202, v203
	v_add_f32_e32 v204, v204, v205
	v_add_f32_e32 v206, v206, v207
	v_mul_f32_e32 v200, 0x3b800000, v200
	v_mul_f32_e32 v202, 0x3b800000, v202
	v_mul_f32_e32 v204, 0x3b800000, v204
	v_mul_f32_e32 v206, 0x3b800000, v206
	v_add_f32_e32 v200, 0x3727c5ac, v200
	v_add_f32_e32 v202, 0x3727c5ac, v202
	v_add_f32_e32 v204, 0x3727c5ac, v204
	v_add_f32_e32 v206, 0x3727c5ac, v206
	v_rsq_f32_e32 v200, v200
	v_rsq_f32_e32 v202, v202
	v_rsq_f32_e32 v204, v204
	v_rsq_f32_e32 v206, v206
	s_nop 0
	v_mul_f32_e32 v200, 0x3e16c740, v200
	v_mul_f32_e32 v204, 0x3e16c740, v204
	ds_write_b32 v208, v200
	ds_write_b32 v208, v202 offset:1088
	v_cmp_gt_u32_e32 vcc, 16, v163
	s_and_saveexec_b64 s[0:1], vcc
	ds_write_b32 v208, v204 offset:1024
	ds_write_b32 v208, v206 offset:2112
	s_mov_b64 exec, s[0:1]
